# idle-slot work re-balancing: next-layer weight conversion parts 0-2 in the G2 slot and parts 3-7 in the G5 slot (was 0-4 / 5-7); on top of v42
# speedup vs baseline: 1.0032x; 1.0032x over previous
; #define LAS __attribute__((address_space(3)))
; DI void conv_weights(const Cx& a, int l, LAS unsigned char* lds, int tid, int gw, int NGW, int p_lo, int p_hi) {
;     ...
;     const int np = p_hi - p_lo;
;     for (int jt = gw; jt < (NITEMS / 8) * np; jt += NGW) {
;         const int it = (jt / np) * 8 + p_lo + jt % np; int r = it;
;         if (r < I_IN) { transpose_item(w_in, INW, (bf16_t*)(wb + WB_IN), DM, 0, r, INW / 32, false, scr, lane); continue; } r -= I_IN;
;         if (r < I_B) { transpose_item(w_br, DM, (bf16_t*)(wb + WB_BR), 1536, 0, r, DM / 32, false, scr, lane); continue; } r -= I_B;
;         if (r < I_B) { transpose_item(w_br + (size_t)2 * 512 * DM, DM, (bf16_t*)(wb + WB_BR), 1536, 1024, r, DM / 32, false, scr, lane); continue; } r -= I_B;
;         if (r < I_O) { transpose_item(w_o, DM, (bf16_t*)(wb + WB_O), DM, 0, r, DM / 32, false, scr, lane); continue; } r -= I_O;
;         if (r < I_FI) { transpose_item(w_fi, 2 * DFF, (bf16_t*)(wb + WB_FI), DM, 0, r, 2 * DFF / 32, true, scr, lane); continue; } r -= I_FI;
;         transpose_item(w_fo, DM, (bf16_t*)(wb + WB_FO), DFF, 0, r, DM / 32, false, scr, lane);
;     }
; DI void phase_conv(const Cx& a, int l, LAS unsigned char* lds, int p_lo, int p_hi) { int tid_ = threadIdx.x; asm volatile("" : "+v"(tid_));
;     const int first = (a.G == 256) ? 64 : 0; if (a.bx < first) return;
;     conv_weights(a, l, lds, tid_, (a.bx - first) * 8 + (tid_ >> 6), (a.G - first) * 8, p_lo, p_hi); }
.LBB0_789:
	s_or_b64 exec, exec, s[16:17]
	v_add_u32_e32 v49, s9, v49
	s_movk_i32 s10, 0xbff
	v_cmp_lt_i32_e32 vcc, s10, v49
	s_or_b64 s[14:15], vcc, s[14:15]
	s_andn2_b64 exec, exec, s[14:15]
	s_cbranch_execz .LBB0_838
.LBB0_790:
	s_mov_b32 s10, 0x55555556
	v_mul_hi_i32 v7, v49, s10
	v_lshrrev_b32_e32 v30, 31, v7
	v_add_u32_e32 v7, v7, v30
	v_lshl_add_u32 v30, v7, 1, v7
	v_sub_u32_e32 v30, v49, v30
	v_lshl_add_u32 v7, v7, 3, v30
	s_movk_i32 s10, 0xb7f
	v_cmp_lt_i32_e32 vcc, s10, v7
	s_and_saveexec_b64 s[16:17], vcc
	s_xor_b64 s[16:17], exec, s[16:17]
	s_cbranch_execz .LBB0_834
	s_movk_i32 s10, 0xc7f
	v_cmp_lt_u32_e32 vcc, s10, v7
	s_and_saveexec_b64 s[18:19], vcc
	s_xor_b64 s[18:19], exec, s[18:19]
	s_cbranch_execz .LBB0_829
	s_movk_i32 s10, 0xd7f
	v_cmp_lt_u32_e32 vcc, s10, v7
	s_and_saveexec_b64 s[20:21], vcc
	s_xor_b64 s[20:21], exec, s[20:21]
	s_cbranch_execz .LBB0_824
	s_movk_i32 s10, 0xf7f
	v_cmp_lt_u32_e32 vcc, s10, v7
	s_and_saveexec_b64 s[22:23], vcc
	s_xor_b64 s[22:23], exec, s[22:23]
	s_cbranch_execz .LBB0_819
	s_movk_i32 s10, 0x1a7f
	v_cmp_lt_u32_e32 vcc, s10, v7
	s_and_saveexec_b64 s[24:25], vcc
	s_xor_b64 s[24:25], exec, s[24:25]
	s_cbranch_execz .LBB0_798
	v_lshlrev_b32_e32 v30, 1, v7
	v_lshlrev_b32_e32 v7, 5, v7
	v_and_b32_e32 v30, 0x7fffffc0, v30
	v_and_b32_e32 v35, 0x3e0, v7
	v_add_u32_e32 v30, 0xffffcb00, v30
	v_lshlrev_b32_e32 v96, 2, v35
	s_mov_b32 s10, 1
	v_lshl_add_u64 v[32:33], v[4:5], 0, v[96:97]
	v_or_b32_e32 v7, v3, v30
	v_or_b32_e32 v34, v2, v30
	s_mov_b32 s26, 0
	s_mov_b32 s27, 32

; DI unsigned f2bf(float f) { unsigned u = __float_as_uint(f); return (u + 0x7fffu + ((u >> 16) & 1u)) >> 16; }
; DI void conv_weights(const Cx& a, int l, LAS unsigned char* lds, int tid, int gw, int NGW, int p_lo, int p_hi) {
;     ...
;     for (int jt = gw; jt < (512 * (DM / 64) / 8) * np; jt += NGW) { const int it = (jt / np) * 8 + p_lo + jt % np;
;         const int kc = it >> 4, n = (it & 15) * 64 + lane, g = kc >> 7; const float* wrow = wp + (size_t)kc * 128; const float* pss = psc + g * 128; const float* wbc = wb1 + (size_t)(g * 128) * DM + n;
;         float s0 = 0.f, s1 = 0.f, s2 = 0.f, s3 = 0.f;
; #pragma unroll 4
;         for (int d = 0; d < 128; d += 4) {
;             s0 += wrow[d] * pss[d] * wbc[(size_t)d * DM]; s1 += wrow[d + 1] * pss[d + 1] * wbc[(size_t)(d + 1) * DM];
;             s2 += wrow[d + 2] * pss[d + 2] * wbc[(size_t)(d + 2) * DM]; s3 += wrow[d + 3] * pss[d + 3] * wbc[(size_t)(d + 3) * DM]; }
;         WbT[(size_t)n * 1536 + 512 + kc] = (bf16_t)f2bf((s0 + s1) + (s2 + s3));
;     }
.LBB0_839:
	s_mov_b32 s10, 0x55555556
	v_mul_hi_i32 v8, v42, s10
	v_lshrrev_b32_e32 v9, 31, v8
	v_add_u32_e32 v8, v8, v9
	v_lshl_add_u32 v9, v8, 1, v8
	v_sub_u32_e32 v9, v42, v9
	v_lshl_add_u32 v9, v8, 3, v9
	v_ashrrev_i32_e32 v8, 4, v9
	v_lshlrev_b32_e32 v9, 6, v9
	s_movk_i32 s10, 0x3c0
	v_and_b32_e32 v14, 0xffffff80, v8
	v_and_or_b32 v30, v9, s10, v43
	v_ashrrev_i32_e32 v9, 31, v8
	v_ashrrev_i32_e32 v15, 31, v14
	v_lshlrev_b64 v[16:17], 9, v[8:9]
	v_lshlrev_b64 v[12:13], 12, v[14:15]
	v_mov_b32_e32 v22, 0
	v_lshlrev_b32_e32 v96, 2, v30
	v_lshl_add_u64 v[10:11], v[2:3], 0, v[12:13]
	v_lshl_add_u64 v[12:13], v[0:1], 0, v[12:13]
	v_lshl_add_u64 v[14:15], v[14:15], 2, v[4:5]
	v_lshl_add_u64 v[16:17], v[6:7], 0, v[16:17]
	s_mov_b32 s10, -4
	s_mov_b64 s[14:15], 0
	v_mov_b32_e32 v23, v22
	v_mov_b32_e32 v24, v22
	v_mov_b32_e32 v25, v22
.LBB0_840:
	v_lshl_add_u64 v[36:37], v[12:13], 0, v[96:97]
	v_add_co_u32_e32 v26, vcc, 0x800000, v36
	v_lshl_add_u64 v[20:21], v[16:17], 0, s[14:15]
	s_nop 0
	v_addc_co_u32_e32 v27, vcc, 0, v37, vcc
	flat_load_dword v38, v[26:27]
	v_add_co_u32_e32 v26, vcc, 0x801000, v36
	v_lshl_add_u64 v[18:19], v[14:15], 0, s[14:15]
	s_nop 0
	v_addc_co_u32_e32 v27, vcc, 0, v37, vcc
	flat_load_dword v40, v[26:27]
	v_add_co_u32_e32 v26, vcc, 0x802000, v36
	s_mov_b32 s16, 0x804000
	s_nop 0
	v_addc_co_u32_e32 v27, vcc, 0, v37, vcc
	flat_load_dword v39, v[26:27]
	v_add_co_u32_e32 v26, vcc, 0x803000, v36
	s_add_i32 s10, s10, 16
	s_nop 0
	v_addc_co_u32_e32 v27, vcc, 0, v37, vcc
	flat_load_dword v41, v[26:27]
	s_nop 0
	flat_load_dwordx4 v[26:29], v[20:21]
	flat_load_dwordx4 v[32:35], v[18:19] offset:2048
	s_add_u32 s14, s14, 64
	s_addc_u32 s15, s15, 0
	v_lshl_add_u64 v[12:13], v[12:13], 0, s[96:97]
	s_cmpk_gt_u32 s10, 0x7b
	s_waitcnt vmcnt(0) lgkmcnt(0)
	v_pk_mul_f32 v[28:29], v[28:29], v[34:35]
	v_pk_mul_f32 v[26:27], v[26:27], v[32:33]
	v_mov_b32_e32 v33, v28
	v_mov_b32_e32 v32, v26
	v_pk_fma_f32 v[32:33], v[32:33], v[38:39], v[22:23]
	v_add_co_u32_e32 v22, vcc, s16, v36
	s_mov_b32 s16, 0x805000
	s_nop 0
	v_addc_co_u32_e32 v23, vcc, 0, v37, vcc
	flat_load_dword v38, v[22:23]
	v_add_co_u32_e32 v22, vcc, s16, v36
	v_mov_b32_e32 v28, v27
	s_nop 0
	v_addc_co_u32_e32 v23, vcc, 0, v37, vcc
	s_mov_b32 s16, 0x806000
	v_pk_fma_f32 v[34:35], v[28:29], v[40:41], v[24:25]
	flat_load_dword v40, v[22:23]
	v_add_co_u32_e32 v22, vcc, s16, v36
	s_mov_b32 s16, 0x807000
	s_nop 0
	v_addc_co_u32_e32 v23, vcc, 0, v37, vcc
	flat_load_dword v39, v[22:23]
	v_add_co_u32_e32 v22, vcc, s16, v36
	s_mov_b32 s16, 0x808000
	s_nop 0
	v_addc_co_u32_e32 v23, vcc, 0, v37, vcc
	flat_load_dword v41, v[22:23]
	s_nop 0
	flat_load_dwordx4 v[22:25], v[20:21] offset:16
	flat_load_dwordx4 v[26:29], v[18:19] offset:2064
	s_waitcnt vmcnt(0) lgkmcnt(0)
	v_pk_mul_f32 v[22:23], v[22:23], v[26:27]
	v_pk_mul_f32 v[24:25], v[24:25], v[28:29]
	v_mov_b32_e32 v26, v22
	v_add_co_u32_e32 v22, vcc, s16, v36
	v_mov_b32_e32 v27, v24
	v_mov_b32_e32 v24, v23
	v_addc_co_u32_e32 v23, vcc, 0, v37, vcc
	s_mov_b32 s16, 0x809000
	v_pk_fma_f32 v[32:33], v[26:27], v[38:39], v[32:33]
	flat_load_dword v38, v[22:23]
	v_add_co_u32_e32 v22, vcc, s16, v36
	s_mov_b32 s16, 0x80a000
	s_nop 0
	v_addc_co_u32_e32 v23, vcc, 0, v37, vcc
	v_pk_fma_f32 v[34:35], v[24:25], v[40:41], v[34:35]
	flat_load_dword v40, v[22:23]
	v_add_co_u32_e32 v22, vcc, s16, v36
	s_mov_b32 s16, 0x80b000
	s_nop 0
	v_addc_co_u32_e32 v23, vcc, 0, v37, vcc
	flat_load_dword v39, v[22:23]
	v_add_co_u32_e32 v22, vcc, s16, v36
	s_mov_b32 s16, 0x80c000
	s_nop 0
	v_addc_co_u32_e32 v23, vcc, 0, v37, vcc
	flat_load_dword v41, v[22:23]
	s_nop 0
	flat_load_dwordx4 v[22:25], v[20:21] offset:32
	flat_load_dwordx4 v[26:29], v[18:19] offset:2080
	s_waitcnt vmcnt(0) lgkmcnt(0)
	v_pk_mul_f32 v[24:25], v[24:25], v[28:29]
	v_pk_mul_f32 v[22:23], v[22:23], v[26:27]
	v_mov_b32_e32 v27, v24
	v_mov_b32_e32 v26, v22
	v_mov_b32_e32 v24, v23
	v_pk_fma_f32 v[22:23], v[26:27], v[38:39], v[32:33]
	v_add_co_u32_e32 v26, vcc, s16, v36
	s_mov_b32 s16, 0x80d000
	s_nop 0
	v_addc_co_u32_e32 v27, vcc, 0, v37, vcc
	v_add_co_u32_e32 v28, vcc, s16, v36
	s_mov_b32 s16, 0x80e000
	s_nop 0
	v_addc_co_u32_e32 v29, vcc, 0, v37, vcc
	v_add_co_u32_e32 v32, vcc, s16, v36
	flat_load_dword v26, v[26:27]
	s_nop 0
	v_addc_co_u32_e32 v33, vcc, 0, v37, vcc
	flat_load_dword v28, v[28:29]
	v_pk_fma_f32 v[24:25], v[24:25], v[40:41], v[34:35]
	flat_load_dword v27, v[32:33]
	v_lshl_add_u64 v[32:33], v[10:11], 0, v[96:97]
	flat_load_dword v29, v[32:33]
	s_nop 0
	flat_load_dwordx4 v[32:35], v[20:21] offset:48
	s_nop 0
	flat_load_dwordx4 v[18:21], v[18:19] offset:2096
	v_lshl_add_u64 v[10:11], v[10:11], 0, s[96:97]
	s_waitcnt vmcnt(0) lgkmcnt(0)
	v_pk_mul_f32 v[20:21], v[34:35], v[20:21]
	v_pk_mul_f32 v[18:19], v[32:33], v[18:19]
	v_mov_b32_e32 v33, v20
	v_mov_b32_e32 v32, v18
	v_mov_b32_e32 v20, v19
	v_pk_fma_f32 v[22:23], v[32:33], v[26:27], v[22:23]
	v_pk_fma_f32 v[24:25], v[20:21], v[28:29], v[24:25]
	s_cbranch_scc0 .LBB0_840
	v_pk_add_f32 v[10:11], v[22:23], v[24:25]
	s_movk_i32 s10, 0xc00
	v_pk_add_f32 v[10:11], v[10:11], v[10:11] op_sel:[0,1] op_sel_hi:[1,0]
	v_add_u32_e32 v42, s9, v42
	v_bfe_u32 v11, v10, 16, 1
	v_add3_u32 v12, v10, v11, s40
	v_mov_b64_e32 v[10:11], s[4:5]
	v_mad_u64_u32 v[10:11], s[14:15], v30, s10, v[10:11]
	s_movk_i32 s10, 0xbff
	v_cmp_lt_i32_e32 vcc, s10, v42
	v_lshl_add_u64 v[8:9], v[8:9], 1, v[10:11]
	s_or_b64 s[6:7], vcc, s[6:7]
	global_store_short_d16_hi v[8:9], v12, off
	s_andn2_b64 exec, exec, s[6:7]
	s_cbranch_execnz .LBB0_839

; #define LAS __attribute__((address_space(3)))
; DI void conv_weights(const Cx& a, int l, LAS unsigned char* lds, int tid, int gw, int NGW, int p_lo, int p_hi) {
;     ...
;     const int np = p_hi - p_lo;
;     for (int jt = gw; jt < (NITEMS / 8) * np; jt += NGW) {
;         const int it = (jt / np) * 8 + p_lo + jt % np; int r = it;
;         if (r < I_IN) { transpose_item(w_in, INW, (bf16_t*)(wb + WB_IN), DM, 0, r, INW / 32, false, scr, lane); continue; } r -= I_IN;
;         if (r < I_B) { transpose_item(w_br, DM, (bf16_t*)(wb + WB_BR), 1536, 0, r, DM / 32, false, scr, lane); continue; } r -= I_B;
;         if (r < I_B) { transpose_item(w_br + (size_t)2 * 512 * DM, DM, (bf16_t*)(wb + WB_BR), 1536, 1024, r, DM / 32, false, scr, lane); continue; } r -= I_B;
;         if (r < I_O) { transpose_item(w_o, DM, (bf16_t*)(wb + WB_O), DM, 0, r, DM / 32, false, scr, lane); continue; } r -= I_O;
;         if (r < I_FI) { transpose_item(w_fi, 2 * DFF, (bf16_t*)(wb + WB_FI), DM, 0, r, 2 * DFF / 32, true, scr, lane); continue; } r -= I_FI;
;         transpose_item(w_fo, DM, (bf16_t*)(wb + WB_FO), DFF, 0, r, DM / 32, false, scr, lane);
;     }
; DI void phase_conv(const Cx& a, int l, LAS unsigned char* lds, int p_lo, int p_hi) { int tid_ = threadIdx.x; asm volatile("" : "+v"(tid_));
;     const int first = (a.G == 256) ? 64 : 0; if (a.bx < first) return;
;     conv_weights(a, l, lds, tid_, (a.bx - first) * 8 + (tid_ >> 6), (a.G - first) * 8, p_lo, p_hi); }
.LBB0_1150:
	s_or_b64 exec, exec, s[16:17]
	v_add_u32_e32 v45, s10, v45
	s_movk_i32 s14, 0x13ff
	v_cmp_lt_i32_e32 vcc, s14, v45
	s_or_b64 s[8:9], vcc, s[8:9]
	s_andn2_b64 exec, exec, s[8:9]
	s_cbranch_execz .LBB0_1199
.LBB0_1151:
	s_mov_b32 s14, 0x66666667
	v_mul_hi_i32 v5, v45, s14
	v_lshrrev_b32_e32 v28, 31, v5
	v_ashrrev_i32_e32 v5, 1, v5
	v_add_u32_e32 v5, v5, v28
	v_lshlrev_b32_e32 v28, 3, v5
	v_lshl_add_u32 v5, v5, 2, v5
	v_sub_u32_e32 v5, v45, v5
	v_add3_u32 v5, v5, v28, 3
	s_movk_i32 s14, 0xb7f
	v_cmp_lt_i32_e32 vcc, s14, v5
	s_and_saveexec_b64 s[14:15], vcc
	s_xor_b64 s[16:17], exec, s[14:15]
	s_cbranch_execz .LBB0_1195
	s_movk_i32 s14, 0xc7f
	v_cmp_lt_u32_e32 vcc, s14, v5
	s_and_saveexec_b64 s[14:15], vcc
	s_xor_b64 s[18:19], exec, s[14:15]
	s_cbranch_execz .LBB0_1190
	s_movk_i32 s14, 0xd7f
	v_cmp_lt_u32_e32 vcc, s14, v5
	s_and_saveexec_b64 s[14:15], vcc
	s_xor_b64 s[20:21], exec, s[14:15]
	s_cbranch_execz .LBB0_1185
	s_movk_i32 s14, 0xf7f
	v_cmp_lt_u32_e32 vcc, s14, v5
	s_and_saveexec_b64 s[14:15], vcc
	s_xor_b64 s[22:23], exec, s[14:15]
	s_cbranch_execz .LBB0_1180
	s_movk_i32 s14, 0x1a7f
	v_cmp_lt_u32_e32 vcc, s14, v5
	s_and_saveexec_b64 s[14:15], vcc
	s_xor_b64 s[24:25], exec, s[14:15]
	s_cbranch_execz .LBB0_1159
	v_lshlrev_b32_e32 v28, 1, v5
	v_lshlrev_b32_e32 v5, 5, v5
	v_and_b32_e32 v28, 0x7fffffc0, v28
	v_and_b32_e32 v33, 0x3e0, v5
	v_add_u32_e32 v28, 0xffffcb00, v28
	v_lshlrev_b32_e32 v96, 2, v33
	s_mov_b32 s14, 1
	v_lshl_add_u64 v[30:31], v[2:3], 0, v[96:97]
	v_or_b32_e32 v5, v1, v28
	v_or_b32_e32 v32, v0, v28
	s_mov_b32 s15, 0
	s_mov_b32 s26, 32

; DI unsigned f2bf(float f) { unsigned u = __float_as_uint(f); return (u + 0x7fffu + ((u >> 16) & 1u)) >> 16; }
; DI void conv_weights(const Cx& a, int l, LAS unsigned char* lds, int tid, int gw, int NGW, int p_lo, int p_hi) {
;     ...
;     for (int jt = gw; jt < (512 * (DM / 64) / 8) * np; jt += NGW) { const int it = (jt / np) * 8 + p_lo + jt % np;
;         const int kc = it >> 4, n = (it & 15) * 64 + lane, g = kc >> 7; const float* wrow = wp + (size_t)kc * 128; const float* pss = psc + g * 128; const float* wbc = wb1 + (size_t)(g * 128) * DM + n;
;         float s0 = 0.f, s1 = 0.f, s2 = 0.f, s3 = 0.f;
; #pragma unroll 4
;         for (int d = 0; d < 128; d += 4) {
;             s0 += wrow[d] * pss[d] * wbc[(size_t)d * DM]; s1 += wrow[d + 1] * pss[d + 1] * wbc[(size_t)(d + 1) * DM];
;             s2 += wrow[d + 2] * pss[d + 2] * wbc[(size_t)(d + 2) * DM]; s3 += wrow[d + 3] * pss[d + 3] * wbc[(size_t)(d + 3) * DM]; }
;         WbT[(size_t)n * 1536 + 512 + kc] = (bf16_t)f2bf((s0 + s1) + (s2 + s3));
;     }
.LBB0_1200:
	s_mov_b32 s14, 0x66666667
	v_mul_hi_i32 v4, v50, s14
	v_lshrrev_b32_e32 v5, 31, v4
	v_ashrrev_i32_e32 v4, 1, v4
	v_add_u32_e32 v4, v4, v5
	v_lshlrev_b32_e32 v5, 3, v4
	v_lshl_add_u32 v4, v4, 2, v4
	v_sub_u32_e32 v4, v50, v4
	v_add3_u32 v5, v4, v5, 3
	v_ashrrev_i32_e32 v4, 4, v5
	v_lshlrev_b32_e32 v5, 6, v5
	s_movk_i32 s14, 0x3c0
	v_and_b32_e32 v38, 0xffffff80, v4
	v_and_or_b32 v52, v5, s14, v51
	v_ashrrev_i32_e32 v5, 31, v4
	v_ashrrev_i32_e32 v39, 31, v38
	v_lshlrev_b64 v[40:41], 9, v[4:5]
	v_lshlrev_b64 v[36:37], 12, v[38:39]
	v_mov_b32_e32 v42, 0
	v_lshlrev_b32_e32 v96, 2, v52
	v_lshl_add_u64 v[6:7], s[6:7], 0, v[36:37]
	v_lshl_add_u64 v[8:9], s[8:9], 0, v[36:37]
	v_lshl_add_u64 v[10:11], s[16:17], 0, v[36:37]
	v_lshl_add_u64 v[12:13], s[18:19], 0, v[36:37]
	v_lshl_add_u64 v[14:15], s[20:21], 0, v[36:37]
	v_lshl_add_u64 v[16:17], s[22:23], 0, v[36:37]
	v_lshl_add_u64 v[18:19], s[24:25], 0, v[36:37]
	v_lshl_add_u64 v[20:21], s[26:27], 0, v[36:37]
	v_lshl_add_u64 v[22:23], s[28:29], 0, v[36:37]
	v_lshl_add_u64 v[24:25], s[30:31], 0, v[36:37]
	v_lshl_add_u64 v[26:27], s[52:53], 0, v[36:37]
	v_lshl_add_u64 v[28:29], s[54:55], 0, v[36:37]
	v_lshl_add_u64 v[30:31], s[72:73], 0, v[36:37]
	v_lshl_add_u64 v[32:33], s[74:75], 0, v[36:37]
	v_lshl_add_u64 v[34:35], s[76:77], 0, v[36:37]
	v_lshl_add_u64 v[36:37], s[78:79], 0, v[36:37]
	v_lshl_add_u64 v[38:39], v[38:39], 2, v[0:1]
	v_lshl_add_u64 v[40:41], v[2:3], 0, v[40:41]
	s_mov_b32 s14, -4
	s_mov_b64 s[82:83], 0
	v_mov_b32_e32 v43, v42
	v_mov_b32_e32 v44, v42
	v_mov_b32_e32 v45, v42
.LBB0_1201:
	v_lshl_add_u64 v[54:55], v[36:37], 0, v[96:97]
	flat_load_dword v62, v[54:55]
	v_lshl_add_u64 v[54:55], v[34:35], 0, v[96:97]
	flat_load_dword v64, v[54:55]
	v_lshl_add_u64 v[54:55], v[32:33], 0, v[96:97]
	flat_load_dword v63, v[54:55]
	v_lshl_add_u64 v[54:55], v[30:31], 0, v[96:97]
	v_lshl_add_u64 v[46:47], v[40:41], 0, s[82:83]
	v_lshl_add_u64 v[48:49], v[38:39], 0, s[82:83]
	flat_load_dword v65, v[54:55]
	s_nop 0
	flat_load_dwordx4 v[54:57], v[46:47]
	flat_load_dwordx4 v[58:61], v[48:49] offset:2048
	s_add_i32 s14, s14, 16
	s_add_u32 s82, s82, 64
	s_addc_u32 s83, s83, 0
	v_lshl_add_u64 v[30:31], v[30:31], 0, s[96:97]
	v_lshl_add_u64 v[32:33], v[32:33], 0, s[96:97]
	v_lshl_add_u64 v[34:35], v[34:35], 0, s[96:97]
	v_lshl_add_u64 v[36:37], v[36:37], 0, s[96:97]
	s_cmpk_gt_u32 s14, 0x7b
	s_waitcnt vmcnt(0) lgkmcnt(0)
	v_pk_mul_f32 v[56:57], v[56:57], v[60:61]
	v_pk_mul_f32 v[54:55], v[54:55], v[58:59]
	v_mov_b32_e32 v59, v56
	v_mov_b32_e32 v58, v54
	v_pk_fma_f32 v[58:59], v[58:59], v[62:63], v[42:43]
	v_lshl_add_u64 v[42:43], v[28:29], 0, v[96:97]
	v_mov_b32_e32 v56, v55
	flat_load_dword v62, v[42:43]
	v_lshl_add_u64 v[42:43], v[26:27], 0, v[96:97]
	v_pk_fma_f32 v[60:61], v[56:57], v[64:65], v[44:45]
	flat_load_dword v64, v[42:43]
	v_lshl_add_u64 v[42:43], v[24:25], 0, v[96:97]
	flat_load_dword v63, v[42:43]
	v_lshl_add_u64 v[42:43], v[22:23], 0, v[96:97]
	flat_load_dword v65, v[42:43]
	s_nop 0
	flat_load_dwordx4 v[42:45], v[46:47] offset:16
	flat_load_dwordx4 v[54:57], v[48:49] offset:2064
	v_lshl_add_u64 v[22:23], v[22:23], 0, s[96:97]
	v_lshl_add_u64 v[24:25], v[24:25], 0, s[96:97]
	v_lshl_add_u64 v[26:27], v[26:27], 0, s[96:97]
	v_lshl_add_u64 v[28:29], v[28:29], 0, s[96:97]
	s_waitcnt vmcnt(0) lgkmcnt(0)
	v_pk_mul_f32 v[44:45], v[44:45], v[56:57]
	v_pk_mul_f32 v[42:43], v[42:43], v[54:55]
	v_mov_b32_e32 v55, v44
	v_mov_b32_e32 v54, v42
	v_mov_b32_e32 v44, v43
	v_lshl_add_u64 v[42:43], v[20:21], 0, v[96:97]
	v_pk_fma_f32 v[58:59], v[54:55], v[62:63], v[58:59]
	flat_load_dword v62, v[42:43]
	v_lshl_add_u64 v[42:43], v[18:19], 0, v[96:97]
	v_pk_fma_f32 v[60:61], v[44:45], v[64:65], v[60:61]
	flat_load_dword v64, v[42:43]
	v_lshl_add_u64 v[42:43], v[16:17], 0, v[96:97]
	flat_load_dword v63, v[42:43]
	v_lshl_add_u64 v[42:43], v[14:15], 0, v[96:97]
	flat_load_dword v65, v[42:43]
	s_nop 0
	flat_load_dwordx4 v[42:45], v[46:47] offset:32
	flat_load_dwordx4 v[54:57], v[48:49] offset:2080
	v_lshl_add_u64 v[14:15], v[14:15], 0, s[96:97]
	v_lshl_add_u64 v[16:17], v[16:17], 0, s[96:97]
	v_lshl_add_u64 v[18:19], v[18:19], 0, s[96:97]
	v_lshl_add_u64 v[20:21], v[20:21], 0, s[96:97]
	s_waitcnt vmcnt(0) lgkmcnt(0)
	v_pk_mul_f32 v[44:45], v[44:45], v[56:57]
	v_pk_mul_f32 v[42:43], v[42:43], v[54:55]
	v_mov_b32_e32 v55, v44
	v_mov_b32_e32 v54, v42
	v_mov_b32_e32 v44, v43
	v_lshl_add_u64 v[42:43], v[12:13], 0, v[96:97]
	v_pk_fma_f32 v[54:55], v[54:55], v[62:63], v[58:59]
	flat_load_dword v58, v[42:43]
	v_lshl_add_u64 v[42:43], v[10:11], 0, v[96:97]
	v_pk_fma_f32 v[56:57], v[44:45], v[64:65], v[60:61]
	flat_load_dword v60, v[42:43]
	v_lshl_add_u64 v[42:43], v[8:9], 0, v[96:97]
	flat_load_dword v59, v[42:43]
	v_lshl_add_u64 v[42:43], v[6:7], 0, v[96:97]
	flat_load_dword v61, v[42:43]
	s_nop 0
	flat_load_dwordx4 v[42:45], v[46:47] offset:48
	s_nop 0
	flat_load_dwordx4 v[46:49], v[48:49] offset:2096
	v_lshl_add_u64 v[6:7], v[6:7], 0, s[96:97]
	v_lshl_add_u64 v[8:9], v[8:9], 0, s[96:97]
	v_lshl_add_u64 v[10:11], v[10:11], 0, s[96:97]
	v_lshl_add_u64 v[12:13], v[12:13], 0, s[96:97]
	s_waitcnt vmcnt(0) lgkmcnt(0)
	v_pk_mul_f32 v[44:45], v[44:45], v[48:49]
	v_pk_mul_f32 v[42:43], v[42:43], v[46:47]
	v_mov_b32_e32 v47, v44
	v_mov_b32_e32 v46, v42
	v_mov_b32_e32 v44, v43
	v_pk_fma_f32 v[42:43], v[46:47], v[58:59], v[54:55]
	v_pk_fma_f32 v[44:45], v[44:45], v[60:61], v[56:57]
	s_cbranch_scc0 .LBB0_1201
	v_pk_add_f32 v[6:7], v[42:43], v[44:45]
	s_movk_i32 s14, 0xc00
	v_pk_add_f32 v[6:7], v[6:7], v[6:7] op_sel:[0,1] op_sel_hi:[1,0]
	v_add_u32_e32 v50, s10, v50
	v_bfe_u32 v7, v6, 16, 1
	v_add3_u32 v8, v6, v7, s40
	v_mov_b64_e32 v[6:7], s[4:5]
	v_mad_u64_u32 v[6:7], s[14:15], v52, s14, v[6:7]
	s_movk_i32 s14, 0x13ff
	s_nop 0
	v_cmp_lt_i32_e32 vcc, s14, v50
	v_lshl_add_u64 v[4:5], v[4:5], 1, v[6:7]
	s_or_b64 s[80:81], vcc, s[80:81]
	global_store_short_d16_hi v[4:5], v8, off
	s_andn2_b64 exec, exec, s[80:81]
	s_cbranch_execnz .LBB0_1200
